# ATTN K-row reduction via DPP instead of 8 ds_bpermute round trips (on top of SCAN + GEMV pipelines)
# baseline (speedup 1.0000x reference)
.LBB0_328:
	s_andn2_b64 vcc, exec, s[20:21]
	s_mov_b64 s[20:21], -1
	s_cbranch_vccnz .LBB0_325
	global_load_dwordx4 v[68:71], v[146:147], off
	global_load_dwordx4 v[64:67], v[146:147], off offset:16
	s_waitcnt vmcnt(5)
	v_and_b32_e32 v73, 0xffff0000, v99
	v_and_b32_e32 v75, 0xffff0000, v98
	v_and_b32_e32 v77, 0xffff0000, v97
	v_and_b32_e32 v79, 0xffff0000, v96
	v_lshlrev_b32_e32 v72, 16, v99
	v_lshlrev_b32_e32 v74, 16, v98
	v_lshlrev_b32_e32 v76, 16, v97
	v_lshlrev_b32_e32 v78, 16, v96
	v_mov_b32_e32 v90, v73
	v_mov_b32_e32 v91, v75
	v_mov_b32_e32 v94, v79
	v_mov_b32_e32 v95, v77
	v_mov_b32_e32 v88, v72
	v_mov_b32_e32 v89, v74
	v_mov_b32_e32 v92, v78
	v_mov_b32_e32 v93, v76
	v_pk_mul_f32 v[90:91], v[90:91], v[90:91]
	v_pk_mul_f32 v[94:95], v[94:95], v[94:95]
	s_waitcnt vmcnt(4)
	v_and_b32_e32 v85, 0xffff0000, v101
	v_and_b32_e32 v87, 0xffff0000, v100
	v_pk_fma_f32 v[88:89], v[88:89], v[88:89], v[90:91]
	v_pk_fma_f32 v[90:91], v[92:93], v[92:93], v[94:95]
	v_and_b32_e32 v81, 0xffff0000, v103
	v_and_b32_e32 v83, 0xffff0000, v102
	v_lshlrev_b32_e32 v84, 16, v101
	v_lshlrev_b32_e32 v86, 16, v100
	v_mov_b32_e32 v174, v87
	v_mov_b32_e32 v175, v85
	v_add_f32_e32 v90, v90, v91
	v_lshlrev_b32_e32 v80, 16, v103
	v_lshlrev_b32_e32 v82, 16, v102
	v_mov_b32_e32 v170, v81
	v_mov_b32_e32 v171, v83
	v_mov_b32_e32 v172, v86
	v_mov_b32_e32 v173, v84
	v_pk_mul_f32 v[174:175], v[174:175], v[174:175]
	v_add_f32_e32 v89, v89, v90
	v_mov_b32_e32 v166, v80
	v_mov_b32_e32 v167, v82
	v_pk_mul_f32 v[170:171], v[170:171], v[170:171]
	v_pk_fma_f32 v[94:95], v[172:173], v[172:173], v[174:175]
	v_add_f32_e32 v88, v88, v89
	v_pk_fma_f32 v[92:93], v[166:167], v[166:167], v[170:171]
	v_add_f32_e32 v91, v94, v95
	v_add_f32_e32 v90, v93, v91
	v_add_f32_e32 v90, v92, v90
	s_add_i32 s20, s41, s48
	s_cmp_eq_u32 s20, 0
	s_nop 0
	v_add_f32_dpp v88, v88, v88 quad_perm:[1,0,3,2] row_mask:0xf bank_mask:0xf
	s_nop 0
	v_add_f32_dpp v90, v90, v90 quad_perm:[1,0,3,2] row_mask:0xf bank_mask:0xf
	s_nop 0
	v_add_f32_dpp v88, v88, v88 quad_perm:[2,3,0,1] row_mask:0xf bank_mask:0xf
	s_nop 0
	v_add_f32_dpp v90, v90, v90 quad_perm:[2,3,0,1] row_mask:0xf bank_mask:0xf
	s_nop 0
	v_add_f32_dpp v88, v88, v88 row_ror:4 row_mask:0xf bank_mask:0xf
	s_nop 0
	v_add_f32_dpp v90, v90, v90 row_ror:4 row_mask:0xf bank_mask:0xf
	s_nop 0
	v_add_f32_dpp v88, v88, v88 row_ror:8 row_mask:0xf bank_mask:0xf
	s_nop 0
	v_add_f32_dpp v90, v90, v90 row_ror:8 row_mask:0xf bank_mask:0xf
	s_nop 0
	v_fmamk_f32 v88, v88, 0x3c000000, v226
	v_rsq_f32_e32 v88, v88
	v_mov_b32_e32 v89, v90
	v_fmamk_f32 v89, v89, 0x3c000000, v226
	v_rsq_f32_e32 v90, v89
	v_pk_mul_f32 v[78:79], v[88:89], v[78:79] op_sel_hi:[0,1]
	v_pk_mul_f32 v[76:77], v[88:89], v[76:77] op_sel_hi:[0,1]
	v_pk_mul_f32 v[74:75], v[88:89], v[74:75] op_sel_hi:[0,1]
	v_pk_mul_f32 v[72:73], v[88:89], v[72:73] op_sel_hi:[0,1]
	s_waitcnt vmcnt(1)
	v_pk_mul_f32 v[78:79], v[68:69], v[78:79]
	v_pk_mul_f32 v[76:77], v[70:71], v[76:77]
	s_waitcnt vmcnt(0)
	v_pk_mul_f32 v[74:75], v[64:65], v[74:75]
	v_pk_mul_f32 v[88:89], v[66:67], v[72:73]
	v_cvt_pk_bf16_f32 v72, v78, v79
	v_cvt_pk_bf16_f32 v73, v76, v77
	v_cvt_pk_bf16_f32 v74, v74, v75
	v_cvt_pk_bf16_f32 v75, v88, v89
	ds_write_b128 v242, v[72:75]
	ds_write_b128 v243, v[104:107] offset:17408
	v_pk_mul_f32 v[72:73], v[90:91], v[86:87] op_sel_hi:[0,1]
	v_pk_mul_f32 v[68:69], v[68:69], v[72:73]
	v_pk_mul_f32 v[72:73], v[90:91], v[84:85] op_sel_hi:[0,1]
	v_pk_mul_f32 v[70:71], v[70:71], v[72:73]
	v_cvt_pk_bf16_f32 v68, v68, v69
	v_cvt_pk_bf16_f32 v69, v70, v71
	v_pk_mul_f32 v[70:71], v[90:91], v[82:83] op_sel_hi:[0,1]
	v_pk_mul_f32 v[64:65], v[64:65], v[70:71]
	s_nop 0
	v_cvt_pk_bf16_f32 v70, v64, v65
	v_pk_mul_f32 v[64:65], v[90:91], v[80:81] op_sel_hi:[0,1]
	v_pk_mul_f32 v[64:65], v[66:67], v[64:65]
	s_nop 0
	v_cvt_pk_bf16_f32 v71, v64, v65
	ds_write_b128 v242, v[68:71] offset:8704
	ds_write_b128 v243, v[108:111] offset:26624
	s_cbranch_scc1 .LBB0_331
	s_add_i32 s30, s19, s48
	s_add_i32 s26, s30, 0x80
	s_lshl_b64 s[20:21], s[26:27], 12
	v_lshl_add_u64 v[64:65], v[158:159], 0, s[20:21]
	s_add_i32 s20, s30, 0xa0
	s_mov_b32 s21, s27
	s_lshl_b64 s[20:21], s[20:21], 12
	v_lshl_add_u64 v[66:67], v[158:159], 0, s[20:21]
	s_lshl_b64 s[20:21], s[26:27], 1
	global_load_dwordx4 v[96:99], v[64:65], off offset:2048
	global_load_dwordx4 v[100:103], v[66:67], off offset:2048
	v_lshl_add_u64 v[64:65], v[160:161], 0, s[20:21]
	v_lshl_add_u64 v[66:67], v[162:163], 0, s[20:21]
	global_load_dwordx4 v[104:107], v[64:65], off
	global_load_dwordx4 v[108:111], v[66:67], off
